# norm2 ctx rows: gain/scale/shift vectors and the row itself loaded in one batch instead of five load-wait rounds (stacked on v140)
# baseline (speedup 1.0000x reference)
.LBB0_758:
	s_add_i32 s0, s4, 0x4000
	s_ashr_i32 s1, s0, 31
	s_lshl_b64 s[0:1], s[0:1], 11
	s_add_i32 s4, s4, s24
	s_cmpk_lt_i32 s4, 0x200
	global_load_dwordx4 v[68:71], v[32:33], off
	global_load_dwordx4 v[84:87], v[36:37], off
	global_load_dwordx4 v[72:75], v[32:33], off offset:1024
	global_load_dwordx4 v[88:91], v[36:37], off offset:1024
	global_load_dwordx4 v[76:79], v[32:33], off offset:2048
	global_load_dwordx4 v[92:95], v[36:37], off offset:2048
	global_load_dwordx4 v[80:83], v[32:33], off offset:3072
	global_load_dwordx4 v[96:99], v[36:37], off offset:3072
	global_load_dwordx4 v[0:3], v[38:39], off
	global_load_dwordx4 v[4:7], v[38:39], off offset:1024
	global_load_dwordx4 v[8:11], v[38:39], off offset:2048
	global_load_dwordx4 v[12:15], v[38:39], off offset:3072
	global_load_dwordx4 v[28:31], v[40:41], off offset:-3072
	global_load_dwordx4 v[24:27], v[40:41], off offset:-2048
	global_load_dwordx4 v[20:23], v[40:41], off offset:-1024
	global_load_dwordx4 v[16:19], v[40:41], off
	s_waitcnt vmcnt(8)
	v_pk_add_f32 v[84:85], v[84:85], 1.0 op_sel_hi:[1,0]
	v_pk_add_f32 v[86:87], v[86:87], 1.0 op_sel_hi:[1,0]
	v_pk_add_f32 v[88:89], v[88:89], 1.0 op_sel_hi:[1,0]
	v_pk_add_f32 v[90:91], v[90:91], 1.0 op_sel_hi:[1,0]
	v_pk_add_f32 v[92:93], v[92:93], 1.0 op_sel_hi:[1,0]
	v_pk_add_f32 v[94:95], v[94:95], 1.0 op_sel_hi:[1,0]
	v_pk_add_f32 v[96:97], v[96:97], 1.0 op_sel_hi:[1,0]
	v_pk_add_f32 v[98:99], v[98:99], 1.0 op_sel_hi:[1,0]
	v_pk_mul_f32 v[42:43], v[70:71], v[86:87]
	v_pk_mul_f32 v[44:45], v[68:69], v[84:85]
	v_pk_mul_f32 v[46:47], v[74:75], v[90:91]
	v_pk_mul_f32 v[48:49], v[72:73], v[88:89]
	v_pk_mul_f32 v[50:51], v[78:79], v[94:95]
	v_pk_mul_f32 v[52:53], v[76:77], v[92:93]
	v_pk_mul_f32 v[54:55], v[82:83], v[98:99]
	v_pk_mul_f32 v[56:57], v[80:81], v[96:97]
	v_lshl_add_u64 v[40:41], v[40:41], 0, s[6:7]
	s_waitcnt vmcnt(3)
	v_pk_mul_f32 v[58:59], v[30:31], v[30:31]
	v_pk_mul_f32 v[60:61], v[28:29], v[28:29]
	v_mov_b32_e32 v63, v59
	v_mov_b32_e32 v62, v60
	v_pk_mov_b32 v[58:59], v[60:61], v[58:59] op_sel:[1,0]
	s_waitcnt vmcnt(2)
	v_pk_mul_f32 v[60:61], v[26:27], v[26:27]
	v_pk_add_f32 v[58:59], v[62:63], v[58:59]
	v_pk_mul_f32 v[62:63], v[24:25], v[24:25]
	v_mov_b32_e32 v65, v61
	v_mov_b32_e32 v64, v62
	v_pk_mov_b32 v[60:61], v[62:63], v[60:61] op_sel:[1,0]
	s_waitcnt vmcnt(0)
	v_mul_f32_e32 v62, v16, v16
	v_pk_add_f32 v[60:61], v[64:65], v[60:61]
	v_mul_f32_e32 v63, v17, v17
	v_pk_add_f32 v[58:59], v[58:59], v[58:59] op_sel:[0,1] op_sel_hi:[1,0]
	v_pk_add_f32 v[60:61], v[60:61], v[60:61] op_sel:[0,1] op_sel_hi:[1,0]
	v_mov_b32_e32 v59, v62
	v_mov_b32_e32 v61, v63
	v_pk_add_f32 v[58:59], v[58:59], v[60:61]
	v_mul_f32_e32 v60, v21, v21
	v_mul_f32_e32 v62, v23, v23
	v_mul_f32_e32 v64, v18, v18
	v_mul_f32_e32 v65, v19, v19
	v_pk_fma_f32 v[60:61], v[20:21], v[20:21], v[60:61] op_sel_hi:[1,1,0]
	v_pk_fma_f32 v[62:63], v[22:23], v[22:23], v[62:63] op_sel_hi:[1,1,0]
	v_mov_b32_e32 v61, v65
	v_mov_b32_e32 v63, v64
	v_pk_add_f32 v[60:61], v[60:61], v[62:63]
	s_nop 0
	v_pk_add_f32 v[58:59], v[58:59], v[60:61]
	v_lshl_add_u64 v[60:61], v[34:35], 0, s[0:1]
	v_add_f32_e32 v58, v58, v59
	v_mbcnt_lo_u32_b32 v59, -1, 0
	v_mbcnt_hi_u32_b32 v59, -1, v59
	s_nop 0
	v_lshlrev_b32_e32 v59, 2, v59
	v_xor_b32_e32 v59, 4, v59
	ds_bpermute_b32 v59, v59, v58
	s_waitcnt lgkmcnt(0)
	v_add_f32_e32 v58, v58, v59
	v_mbcnt_lo_u32_b32 v59, -1, 0
	v_mbcnt_hi_u32_b32 v59, -1, v59
	s_nop 0
	v_lshlrev_b32_e32 v59, 2, v59
	v_xor_b32_e32 v59, 8, v59
	ds_bpermute_b32 v59, v59, v58
	s_waitcnt lgkmcnt(0)
	v_add_f32_e32 v58, v58, v59
	v_mbcnt_lo_u32_b32 v59, -1, 0
	v_mbcnt_hi_u32_b32 v59, -1, v59
	s_nop 0
	v_lshlrev_b32_e32 v59, 2, v59
	v_xor_b32_e32 v59, 16, v59
	ds_bpermute_b32 v59, v59, v58
	s_waitcnt lgkmcnt(0)
	v_add_f32_e32 v58, v58, v59
	v_mbcnt_lo_u32_b32 v59, -1, 0
	v_mbcnt_hi_u32_b32 v59, -1, v59
	s_nop 0
	v_lshlrev_b32_e32 v59, 2, v59
	v_xor_b32_e32 v59, 32, v59
	ds_bpermute_b32 v59, v59, v58
	s_waitcnt lgkmcnt(0)
	v_add_f32_e32 v58, v58, v59
	v_mbcnt_lo_u32_b32 v59, -1, 0
	v_mbcnt_hi_u32_b32 v59, -1, v59
	s_nop 0
	v_lshlrev_b32_e32 v59, 2, v59
	v_xor_b32_e32 v59, 64, v59
	ds_bpermute_b32 v59, v59, v58
	s_waitcnt lgkmcnt(0)
	v_add_f32_e32 v58, v58, v59
	v_mbcnt_lo_u32_b32 v59, -1, 0
	v_mbcnt_hi_u32_b32 v59, -1, v59
	s_nop 0
	v_lshlrev_b32_e32 v59, 2, v59
	v_xor_b32_e32 v59, 0x80, v59
	ds_bpermute_b32 v59, v59, v58
	s_waitcnt lgkmcnt(0)
	v_add_f32_e32 v58, v58, v59
	v_fmamk_f32 v58, v58, 0x3a800000, v208
	v_rsq_f32_e32 v58, v58
	s_nop 0
	v_pk_mul_f32 v[28:29], v[28:29], v[58:59] op_sel_hi:[1,0]
	v_pk_mul_f32 v[30:31], v[30:31], v[58:59] op_sel_hi:[1,0]
	v_pk_fma_f32 v[0:1], v[44:45], v[28:29], v[0:1]
	v_pk_fma_f32 v[2:3], v[42:43], v[30:31], v[2:3]
	v_cvt_pk_bf16_f32 v0, v0, v1
	v_cvt_pk_bf16_f32 v1, v2, v3
	global_store_dwordx2 v[60:61], v[0:1], off
	v_pk_mul_f32 v[0:1], v[24:25], v[58:59] op_sel_hi:[1,0]
	v_pk_mul_f32 v[2:3], v[26:27], v[58:59] op_sel_hi:[1,0]
	v_pk_fma_f32 v[0:1], v[48:49], v[0:1], v[4:5]
	v_pk_fma_f32 v[2:3], v[46:47], v[2:3], v[6:7]
	v_cvt_pk_bf16_f32 v0, v0, v1
	v_cvt_pk_bf16_f32 v1, v2, v3
	global_store_dwordx2 v[60:61], v[0:1], off offset:512
	v_pk_mul_f32 v[0:1], v[20:21], v[58:59] op_sel_hi:[1,0]
	v_pk_mul_f32 v[2:3], v[22:23], v[58:59] op_sel_hi:[1,0]
	v_pk_fma_f32 v[0:1], v[52:53], v[0:1], v[8:9]
	v_pk_fma_f32 v[2:3], v[50:51], v[2:3], v[10:11]
	v_cvt_pk_bf16_f32 v0, v0, v1
	v_cvt_pk_bf16_f32 v1, v2, v3
	global_store_dwordx2 v[60:61], v[0:1], off offset:1024
	v_pk_mul_f32 v[0:1], v[16:17], v[58:59] op_sel_hi:[1,0]
	v_pk_mul_f32 v[2:3], v[18:19], v[58:59] op_sel_hi:[1,0]
	v_pk_fma_f32 v[0:1], v[56:57], v[0:1], v[12:13]
	v_pk_fma_f32 v[2:3], v[54:55], v[2:3], v[14:15]
	v_cvt_pk_bf16_f32 v0, v0, v1
	v_cvt_pk_bf16_f32 v1, v2, v3
	global_store_dwordx2 v[60:61], v[0:1], off offset:1536
	s_cbranch_scc1 .LBB0_758
